# control: attention phase with no static s_setprio raise (everything else as the best version)
# baseline (speedup 1.0000x reference)
; __device__ __forceinline__ void attn_phase(const bf16_t* FQ, const bf16_t* FK, const bf16_t* FV, const float* cum, const float* norms, bf16_t* Y, unsigned* qctr, unsigned* flags, float* parts, lptr lds, int tid_) {
;     ...
;         int tid = tid_; asm volatile("" : "+v"(tid));
;         const int wid = __builtin_amdgcn_readfirstlane(tid >> 6), lane = tid & 63;
.LBB0_820:
	v_readfirstlane_b32 s0, v0
	s_nop 1
	s_cmp_lt_u32 s0, 0x100
	s_cbranch_scc1 .Lattn_prio_done
	s_nop 0
